# v13 + q/k norm gain copy in the prologue de-serialised (4 loads in flight, then 4 stores)
# speedup vs baseline: 1.0075x; 1.0075x over previous
; DI void prologue(KArgs ap, int gw, int NGW, int lane) {
;     ...
;     { unsigned* z = (unsigned*)(ws + WS_X1B); for (int i = gw * 64 + lane; i < 2 * DM / 2; i += NGW * 64) z[i] = 0u;
;       if (gw == 1) { float* gd = (float*)(ws + WS_GAINS); gd[lane] = ap->in[9][lane]; gd[64 + lane] = ap->in[10][lane]; gd[128 + lane] = ap->in[12][lane]; gd[192 + lane] = ap->in[13][lane]; } }
.LBB0_28:
	s_or_b64 exec, exec, s[22:23]
	s_cmp_eq_u32 s6, 1
	v_mov_b32_e32 v3, 0
	s_cbranch_scc0 .LBB0_30
	s_load_dwordx4 s[24:27], s[20:21], 0x48
	s_load_dwordx4 s[28:31], s[20:21], 0x60
	v_lshlrev_b32_e32 v2, 2, v190
	s_waitcnt lgkmcnt(0)
	v_lshl_add_u64 v[4:5], s[16:17], 0, v[2:3]
	v_add_co_u32_e32 v6, vcc, 0x1000, v4
	global_load_dword v1, v2, s[24:25]
	global_load_dword v245, v2, s[26:27]
	global_load_dword v246, v2, s[28:29]
	global_load_dword v247, v2, s[30:31]
	s_nop 0
	v_addc_co_u32_e32 v7, vcc, 0, v5, vcc
	s_mov_b64 s[4:5], 0x1000
	v_lshl_add_u64 v[4:5], v[4:5], 0, s[4:5]
	s_waitcnt vmcnt(0)
	global_store_dword v[6:7], v1, off
	global_store_dword v[4:5], v245, off offset:256
	global_store_dword v[4:5], v246, off offset:512
	global_store_dword v[4:5], v247, off offset:768
